# prologue: removed the cooperative-groups grid.sync at kernel entry (phase 0 has no inter-workgroup dependency; the counter word is zeroed by the host memset before launch), on top of v62
# baseline (speedup 1.0000x reference)
; #define LAS __attribute__((address_space(3)))
; __device__ __forceinline__ void grid_barrier(unsigned* ctr, unsigned target, int wave) {
;     int lane; asm volatile("v_mbcnt_lo_u32_b32 %0, -1, 0\n\tv_mbcnt_hi_u32_b32 %0, -1, %0" : "=v"(lane));
;     asm volatile("s_waitcnt vmcnt(0) lgkmcnt(0)" ::: "memory");
;     __syncthreads();
;     if (wave == 0) {
;         __builtin_amdgcn_fence(__ATOMIC_RELEASE, "agent");
;         if (lane == 0) {
;             __hip_atomic_fetch_add(ctr, 1u, __ATOMIC_RELAXED, __HIP_MEMORY_SCOPE_AGENT);
;             while (__hip_atomic_load(ctr, __ATOMIC_RELAXED, __HIP_MEMORY_SCOPE_AGENT) < target) __builtin_amdgcn_s_sleep(1);
; __global__ void __launch_bounds__(512, 2) mega(Params p, int ph_lo, int ph_hi) {
;     extern __shared__ __attribute__((aligned(16))) unsigned char lds_raw[];
;     LAS unsigned char* lds = (LAS unsigned char*)lds_raw;
;     cg::grid_group grid = cg::this_grid();
;     const int wave = __builtin_amdgcn_readfirstlane(threadIdx.x >> 6);
;     const int G = gridDim.x, bid = blockIdx.x;
;     const int gw = bid * 8 + wave, NGW = G * 8;
;     const int NGT = G * 512;
;     unsigned char* ws = p.ws;
;     bf16_t* WA = (bf16_t*)(ws + WS_WA); bf16_t* WB = (bf16_t*)(ws + WS_WB); bf16_t* W1 = (bf16_t*)(ws + WS_W1); bf16_t* W2 = (bf16_t*)(ws + WS_W2); bf16_t* WG = (bf16_t*)(ws + WS_WG);
;     f32x2* AGG = (f32x2*)(ws + WS_AGG); float* DK = (float*)(ws + WS_DK); float* TAB = (float*)(ws + WS_TAB);
;     bf16_t* XN = (bf16_t*)(ws + WS_XN); bf16_t* BIG = (bf16_t*)(ws + WS_BIG); float* SSQP = (float*)(ws + WS_TAB + 2 * MiB); LAS float* RT = (LAS float*)(lds + pg8::STAGE_BYTES);
;     unsigned* LAU = (unsigned*)(ws + WS_LA); bf16_t* HB = (bf16_t*)(ws + WS_LU);
;     bf16_t* SSTB = (bf16_t*)p.out;
;     grid.sync();
;     int ph = 0, nbar = 0;
;     unsigned* CTR = (unsigned*)(ws + WS_CTR); float* SPT = (float*)(ws + WS_CTR + 4096);
;     ...
;     PHASE_BEGIN
_Z4mega6Paramsii:
	s_load_dwordx8 s[4:11], s[0:1], 0x80
	s_load_dwordx4 s[88:91], s[0:1], 0xa0
	s_load_dword s94, s[0:1], 0xb8
	v_and_b32_e32 v1, 0x3ff, v0
	v_and_b32_e32 v0, 0x3fffffff, v0
	v_readfirstlane_b32 s93, v1
	s_waitcnt lgkmcnt(0)
	v_writelane_b32 v253, s4, 0
	v_cmp_eq_u32_e32 vcc, 0, v0
	s_nop 0
	v_writelane_b32 v253, s5, 1
	v_writelane_b32 v253, s6, 2
	v_writelane_b32 v253, s7, 3
	v_writelane_b32 v253, s8, 4
	v_writelane_b32 v253, s9, 5
	v_writelane_b32 v253, s10, 6
	v_writelane_b32 v253, s11, 7
	s_load_dwordx16 s[56:71], s[0:1], 0x0
	s_load_dwordx16 s[72:87], s[0:1], 0x40
	s_load_dwordx2 s[4:5], s[0:1], 0xb0
	s_lshr_b32 s96, s93, 6
	s_lshl_b32 s0, s2, 3
	s_add_i32 s54, s96, s0
	s_lshl_b32 s92, s94, 3
	s_lshl_b32 s38, s94, 9
	s_add_u32 s36, s90, 0x1800000
	s_addc_u32 s37, s91, 0
	s_add_u32 s0, s90, 0x2000000
	s_addc_u32 s1, s91, 0
	v_writelane_b32 v253, s0, 8
	s_waitcnt lgkmcnt(0)
	v_writelane_b32 v253, s1, 9
	s_add_u32 s0, s90, 0x4000000
	s_addc_u32 s1, s91, 0
	s_add_u32 s14, s90, 0x6000000
	v_writelane_b32 v253, s0, 10
	s_addc_u32 s15, s91, 0
	s_nop 0
	v_writelane_b32 v253, s1, 11
	s_add_u32 s0, s90, 0x6300000
	s_addc_u32 s1, s91, 0
	v_writelane_b32 v253, s0, 12
	s_add_u32 s16, s90, 0x6301000
	s_addc_u32 s17, s91, 0
	v_writelane_b32 v253, s1, 13
	s_mov_b32 s0, 0
	v_writelane_b32 v253, s0, 14
	s_cmp_gt_i32 s4, 0
	s_cselect_b64 s[0:1], -1, 0
	v_writelane_b32 v253, s4, 15
	s_cmp_lt_i32 s5, 1
	s_nop 0
	v_writelane_b32 v253, s5, 16
	s_cselect_b64 s[4:5], -1, 0
	s_or_b64 s[0:1], s[0:1], s[4:5]
	s_and_b64 vcc, exec, s[0:1]
	s_cbranch_vccnz .LBB0_51
	v_readlane_b32 s0, v253, 15
	s_cmp_gt_i32 s0, -1
	s_mov_b32 s0, 0
	v_readlane_b32 s1, v253, 16
	v_writelane_b32 v253, s0, 14
	s_cbranch_scc1 .LBB0_20
	v_mbcnt_lo_u32_b32 v0, -1, 0
	v_mbcnt_hi_u32_b32 v0, -1, v0
	s_waitcnt vmcnt(0) lgkmcnt(0)
	s_cmp_gt_u32 s93, 63
	s_barrier
	s_cbranch_scc1 .LBB0_19
	v_cmp_eq_u32_e32 vcc, 0, v0
	buffer_wbl2 sc1
	s_and_saveexec_b64 s[0:1], vcc
	s_cbranch_execz .LBB0_18
	s_mov_b64 s[6:7], exec
	v_mbcnt_lo_u32_b32 v0, s6, 0
	v_mbcnt_hi_u32_b32 v0, s7, v0
	v_cmp_eq_u32_e32 vcc, 0, v0
	s_and_saveexec_b64 s[4:5], vcc
	s_cbranch_execz .LBB0_16
	s_bcnt1_i32_b64 s3, s[6:7]
	v_readlane_b32 s6, v253, 12
	v_mov_b32_e32 v0, 0
	v_mov_b32_e32 v1, s3
	v_readlane_b32 s7, v253, 13
	s_nop 4
	global_atomic_add v0, v1, s[6:7]
